# also: split-K sample units of oproj/down: gate rows loaded in two batches and all 128 atomics issued without waits (was load, vmcnt(0), 4 atomics, 32 times)
# baseline (speedup 1.0000x reference)
.Lop0_orig:
	s_cmp_lg_u32 s15, 0
	s_cbranch_scc1 .Lop0_done
	v_add_u32_e32 v242, 4, v167
	v_mul_u32_u24_e32 v242, 0x6000, v242
	v_add_u32_e32 v242, v242, v0
	v_lshlrev_b32_e32 v243, 12, v134
	v_add_u32_e32 v243, v243, v0
	global_load_dwordx4 v[130:133], v242, s[6:7] offset:0
	global_load_dwordx4 v[134:137], v242, s[6:7] offset:64
	global_load_dwordx4 v[138:141], v242, s[6:7] offset:128
	global_load_dwordx4 v[142:145], v242, s[6:7] offset:192
	v_add_u32_e32 v242, 0x60000, v242
	global_load_dwordx4 v[146:149], v242, s[6:7] offset:0
	global_load_dwordx4 v[150:153], v242, s[6:7] offset:64
	global_load_dwordx4 v[154:157], v242, s[6:7] offset:128
	global_load_dwordx4 v[158:161], v242, s[6:7] offset:192
	v_add_u32_e32 v242, 0x60000, v242
	global_load_dwordx4 v[162:165], v242, s[6:7] offset:0
	global_load_dwordx4 v[194:197], v242, s[6:7] offset:64
	global_load_dwordx4 v[198:201], v242, s[6:7] offset:128
	global_load_dwordx4 v[202:205], v242, s[6:7] offset:192
	v_add_u32_e32 v242, 0x60000, v242
	global_load_dwordx4 v[206:209], v242, s[6:7] offset:0
	global_load_dwordx4 v[210:213], v242, s[6:7] offset:64
	global_load_dwordx4 v[214:217], v242, s[6:7] offset:128
	global_load_dwordx4 v[218:221], v242, s[6:7] offset:192
	v_add_u32_e32 v242, 0x60000, v242
	s_waitcnt vmcnt(0)
	v_mul_f32_e32 v126, v126, v130
	v_mul_f32_e32 v127, v127, v131
	v_mul_f32_e32 v128, v128, v132
	v_mul_f32_e32 v129, v129, v133
	v_mul_f32_e32 v122, v122, v134
	v_mul_f32_e32 v123, v123, v135
	v_mul_f32_e32 v124, v124, v136
	v_mul_f32_e32 v125, v125, v137
	v_mul_f32_e32 v118, v118, v138
	v_mul_f32_e32 v119, v119, v139
	v_mul_f32_e32 v120, v120, v140
	v_mul_f32_e32 v121, v121, v141
	v_mul_f32_e32 v114, v114, v142
	v_mul_f32_e32 v115, v115, v143
	v_mul_f32_e32 v116, v116, v144
	v_mul_f32_e32 v117, v117, v145
	v_mul_f32_e32 v110, v110, v146
	v_mul_f32_e32 v111, v111, v147
	v_mul_f32_e32 v112, v112, v148
	v_mul_f32_e32 v113, v113, v149
	v_mul_f32_e32 v106, v106, v150
	v_mul_f32_e32 v107, v107, v151
	v_mul_f32_e32 v108, v108, v152
	v_mul_f32_e32 v109, v109, v153
	v_mul_f32_e32 v102, v102, v154
	v_mul_f32_e32 v103, v103, v155
	v_mul_f32_e32 v104, v104, v156
	v_mul_f32_e32 v105, v105, v157
	v_mul_f32_e32 v98, v98, v158
	v_mul_f32_e32 v99, v99, v159
	v_mul_f32_e32 v100, v100, v160
	v_mul_f32_e32 v101, v101, v161
	v_mul_f32_e32 v94, v94, v162
	v_mul_f32_e32 v95, v95, v163
	v_mul_f32_e32 v96, v96, v164
	v_mul_f32_e32 v97, v97, v165
	v_mul_f32_e32 v90, v90, v194
	v_mul_f32_e32 v91, v91, v195
	v_mul_f32_e32 v92, v92, v196
	v_mul_f32_e32 v93, v93, v197
	v_mul_f32_e32 v86, v86, v198
	v_mul_f32_e32 v87, v87, v199
	v_mul_f32_e32 v88, v88, v200
	v_mul_f32_e32 v89, v89, v201
	v_mul_f32_e32 v82, v82, v202
	v_mul_f32_e32 v83, v83, v203
	v_mul_f32_e32 v84, v84, v204
	v_mul_f32_e32 v85, v85, v205
	v_mul_f32_e32 v78, v78, v206
	v_mul_f32_e32 v79, v79, v207
	v_mul_f32_e32 v80, v80, v208
	v_mul_f32_e32 v81, v81, v209
	v_mul_f32_e32 v74, v74, v210
	v_mul_f32_e32 v75, v75, v211
	v_mul_f32_e32 v76, v76, v212
	v_mul_f32_e32 v77, v77, v213
	v_mul_f32_e32 v70, v70, v214
	v_mul_f32_e32 v71, v71, v215
	v_mul_f32_e32 v72, v72, v216
	v_mul_f32_e32 v73, v73, v217
	v_mul_f32_e32 v66, v66, v218
	v_mul_f32_e32 v67, v67, v219
	v_mul_f32_e32 v68, v68, v220
	v_mul_f32_e32 v69, v69, v221
	global_load_dwordx4 v[130:133], v242, s[6:7] offset:0
	global_load_dwordx4 v[134:137], v242, s[6:7] offset:64
	global_load_dwordx4 v[138:141], v242, s[6:7] offset:128
	global_load_dwordx4 v[142:145], v242, s[6:7] offset:192
	v_add_u32_e32 v242, 0x60000, v242
	global_load_dwordx4 v[146:149], v242, s[6:7] offset:0
	global_load_dwordx4 v[150:153], v242, s[6:7] offset:64
	global_load_dwordx4 v[154:157], v242, s[6:7] offset:128
	global_load_dwordx4 v[158:161], v242, s[6:7] offset:192
	v_add_u32_e32 v242, 0x60000, v242
	global_load_dwordx4 v[162:165], v242, s[6:7] offset:0
	global_load_dwordx4 v[194:197], v242, s[6:7] offset:64
	global_load_dwordx4 v[198:201], v242, s[6:7] offset:128
	global_load_dwordx4 v[202:205], v242, s[6:7] offset:192
	v_add_u32_e32 v242, 0x60000, v242
	global_load_dwordx4 v[206:209], v242, s[6:7] offset:0
	global_load_dwordx4 v[210:213], v242, s[6:7] offset:64
	global_load_dwordx4 v[214:217], v242, s[6:7] offset:128
	global_load_dwordx4 v[218:221], v242, s[6:7] offset:192
	v_add_u32_e32 v242, 0x60000, v242
	global_atomic_add_f32 v243, v126, s[82:83] offset:0
	global_atomic_add_f32 v243, v127, s[82:83] offset:4
	global_atomic_add_f32 v243, v128, s[82:83] offset:8
	global_atomic_add_f32 v243, v129, s[82:83] offset:12
	global_atomic_add_f32 v243, v122, s[82:83] offset:64
	global_atomic_add_f32 v243, v123, s[82:83] offset:68
	global_atomic_add_f32 v243, v124, s[82:83] offset:72
	global_atomic_add_f32 v243, v125, s[82:83] offset:76
	global_atomic_add_f32 v243, v118, s[82:83] offset:128
	global_atomic_add_f32 v243, v119, s[82:83] offset:132
	global_atomic_add_f32 v243, v120, s[82:83] offset:136
	global_atomic_add_f32 v243, v121, s[82:83] offset:140
	global_atomic_add_f32 v243, v114, s[82:83] offset:192
	global_atomic_add_f32 v243, v115, s[82:83] offset:196
	global_atomic_add_f32 v243, v116, s[82:83] offset:200
	global_atomic_add_f32 v243, v117, s[82:83] offset:204
	v_add_u32_e32 v243, 0x10000, v243
	global_atomic_add_f32 v243, v110, s[82:83] offset:0
	global_atomic_add_f32 v243, v111, s[82:83] offset:4
	global_atomic_add_f32 v243, v112, s[82:83] offset:8
	global_atomic_add_f32 v243, v113, s[82:83] offset:12
	global_atomic_add_f32 v243, v106, s[82:83] offset:64
	global_atomic_add_f32 v243, v107, s[82:83] offset:68
	global_atomic_add_f32 v243, v108, s[82:83] offset:72
	global_atomic_add_f32 v243, v109, s[82:83] offset:76
	global_atomic_add_f32 v243, v102, s[82:83] offset:128
	global_atomic_add_f32 v243, v103, s[82:83] offset:132
	global_atomic_add_f32 v243, v104, s[82:83] offset:136
	global_atomic_add_f32 v243, v105, s[82:83] offset:140
	global_atomic_add_f32 v243, v98, s[82:83] offset:192
	global_atomic_add_f32 v243, v99, s[82:83] offset:196
	global_atomic_add_f32 v243, v100, s[82:83] offset:200
	global_atomic_add_f32 v243, v101, s[82:83] offset:204
	v_add_u32_e32 v243, 0x10000, v243
	global_atomic_add_f32 v243, v94, s[82:83] offset:0
	global_atomic_add_f32 v243, v95, s[82:83] offset:4
	global_atomic_add_f32 v243, v96, s[82:83] offset:8
	global_atomic_add_f32 v243, v97, s[82:83] offset:12
	global_atomic_add_f32 v243, v90, s[82:83] offset:64
	global_atomic_add_f32 v243, v91, s[82:83] offset:68
	global_atomic_add_f32 v243, v92, s[82:83] offset:72
	global_atomic_add_f32 v243, v93, s[82:83] offset:76
	global_atomic_add_f32 v243, v86, s[82:83] offset:128
	global_atomic_add_f32 v243, v87, s[82:83] offset:132
	global_atomic_add_f32 v243, v88, s[82:83] offset:136
	global_atomic_add_f32 v243, v89, s[82:83] offset:140
	global_atomic_add_f32 v243, v82, s[82:83] offset:192
	global_atomic_add_f32 v243, v83, s[82:83] offset:196
	global_atomic_add_f32 v243, v84, s[82:83] offset:200
	global_atomic_add_f32 v243, v85, s[82:83] offset:204
	v_add_u32_e32 v243, 0x10000, v243
	global_atomic_add_f32 v243, v78, s[82:83] offset:0
	global_atomic_add_f32 v243, v79, s[82:83] offset:4
	global_atomic_add_f32 v243, v80, s[82:83] offset:8
	global_atomic_add_f32 v243, v81, s[82:83] offset:12
	global_atomic_add_f32 v243, v74, s[82:83] offset:64
	global_atomic_add_f32 v243, v75, s[82:83] offset:68
	global_atomic_add_f32 v243, v76, s[82:83] offset:72
	global_atomic_add_f32 v243, v77, s[82:83] offset:76
	global_atomic_add_f32 v243, v70, s[82:83] offset:128
	global_atomic_add_f32 v243, v71, s[82:83] offset:132
	global_atomic_add_f32 v243, v72, s[82:83] offset:136
	global_atomic_add_f32 v243, v73, s[82:83] offset:140
	global_atomic_add_f32 v243, v66, s[82:83] offset:192
	global_atomic_add_f32 v243, v67, s[82:83] offset:196
	global_atomic_add_f32 v243, v68, s[82:83] offset:200
	global_atomic_add_f32 v243, v69, s[82:83] offset:204
	v_add_u32_e32 v243, 0x10000, v243
	s_waitcnt vmcnt(63)
	v_mul_f32_e32 v62, v62, v130
	v_mul_f32_e32 v63, v63, v131
	v_mul_f32_e32 v64, v64, v132
	v_mul_f32_e32 v65, v65, v133
	v_mul_f32_e32 v58, v58, v134
	v_mul_f32_e32 v59, v59, v135
	v_mul_f32_e32 v60, v60, v136
	v_mul_f32_e32 v61, v61, v137
	v_mul_f32_e32 v54, v54, v138
	v_mul_f32_e32 v55, v55, v139
	v_mul_f32_e32 v56, v56, v140
	v_mul_f32_e32 v57, v57, v141
	v_mul_f32_e32 v50, v50, v142
	v_mul_f32_e32 v51, v51, v143
	v_mul_f32_e32 v52, v52, v144
	v_mul_f32_e32 v53, v53, v145
	v_mul_f32_e32 v46, v46, v146
	v_mul_f32_e32 v47, v47, v147
	v_mul_f32_e32 v48, v48, v148
	v_mul_f32_e32 v49, v49, v149
	v_mul_f32_e32 v42, v42, v150
	v_mul_f32_e32 v43, v43, v151
	v_mul_f32_e32 v44, v44, v152
	v_mul_f32_e32 v45, v45, v153
	v_mul_f32_e32 v38, v38, v154
	v_mul_f32_e32 v39, v39, v155
	v_mul_f32_e32 v40, v40, v156
	v_mul_f32_e32 v41, v41, v157
	v_mul_f32_e32 v34, v34, v158
	v_mul_f32_e32 v35, v35, v159
	v_mul_f32_e32 v36, v36, v160
	v_mul_f32_e32 v37, v37, v161
	v_mul_f32_e32 v30, v30, v162
	v_mul_f32_e32 v31, v31, v163
	v_mul_f32_e32 v32, v32, v164
	v_mul_f32_e32 v33, v33, v165
	v_mul_f32_e32 v26, v26, v194
	v_mul_f32_e32 v27, v27, v195
	v_mul_f32_e32 v28, v28, v196
	v_mul_f32_e32 v29, v29, v197
	v_mul_f32_e32 v22, v22, v198
	v_mul_f32_e32 v23, v23, v199
	v_mul_f32_e32 v24, v24, v200
	v_mul_f32_e32 v25, v25, v201
	v_mul_f32_e32 v18, v18, v202
	v_mul_f32_e32 v19, v19, v203
	v_mul_f32_e32 v20, v20, v204
	v_mul_f32_e32 v21, v21, v205
	v_mul_f32_e32 v14, v14, v206
	v_mul_f32_e32 v15, v15, v207
	v_mul_f32_e32 v16, v16, v208
	v_mul_f32_e32 v17, v17, v209
	v_mul_f32_e32 v10, v10, v210
	v_mul_f32_e32 v11, v11, v211
	v_mul_f32_e32 v12, v12, v212
	v_mul_f32_e32 v13, v13, v213
	v_mul_f32_e32 v6, v6, v214
	v_mul_f32_e32 v7, v7, v215
	v_mul_f32_e32 v8, v8, v216
	v_mul_f32_e32 v9, v9, v217
	v_mul_f32_e32 v2, v2, v218
	v_mul_f32_e32 v3, v3, v219
	v_mul_f32_e32 v4, v4, v220
	v_mul_f32_e32 v5, v5, v221
	global_atomic_add_f32 v243, v62, s[82:83] offset:0
	global_atomic_add_f32 v243, v63, s[82:83] offset:4
	global_atomic_add_f32 v243, v64, s[82:83] offset:8
	global_atomic_add_f32 v243, v65, s[82:83] offset:12
	global_atomic_add_f32 v243, v58, s[82:83] offset:64
	global_atomic_add_f32 v243, v59, s[82:83] offset:68
	global_atomic_add_f32 v243, v60, s[82:83] offset:72
	global_atomic_add_f32 v243, v61, s[82:83] offset:76
	global_atomic_add_f32 v243, v54, s[82:83] offset:128
	global_atomic_add_f32 v243, v55, s[82:83] offset:132
	global_atomic_add_f32 v243, v56, s[82:83] offset:136
	global_atomic_add_f32 v243, v57, s[82:83] offset:140
	global_atomic_add_f32 v243, v50, s[82:83] offset:192
	global_atomic_add_f32 v243, v51, s[82:83] offset:196
	global_atomic_add_f32 v243, v52, s[82:83] offset:200
	global_atomic_add_f32 v243, v53, s[82:83] offset:204
	v_add_u32_e32 v243, 0x10000, v243
	global_atomic_add_f32 v243, v46, s[82:83] offset:0
	global_atomic_add_f32 v243, v47, s[82:83] offset:4
	global_atomic_add_f32 v243, v48, s[82:83] offset:8
	global_atomic_add_f32 v243, v49, s[82:83] offset:12
	global_atomic_add_f32 v243, v42, s[82:83] offset:64
	global_atomic_add_f32 v243, v43, s[82:83] offset:68
	global_atomic_add_f32 v243, v44, s[82:83] offset:72
	global_atomic_add_f32 v243, v45, s[82:83] offset:76
	global_atomic_add_f32 v243, v38, s[82:83] offset:128
	global_atomic_add_f32 v243, v39, s[82:83] offset:132
	global_atomic_add_f32 v243, v40, s[82:83] offset:136
	global_atomic_add_f32 v243, v41, s[82:83] offset:140
	global_atomic_add_f32 v243, v34, s[82:83] offset:192
	global_atomic_add_f32 v243, v35, s[82:83] offset:196
	global_atomic_add_f32 v243, v36, s[82:83] offset:200
	global_atomic_add_f32 v243, v37, s[82:83] offset:204
	v_add_u32_e32 v243, 0x10000, v243
	global_atomic_add_f32 v243, v30, s[82:83] offset:0
	global_atomic_add_f32 v243, v31, s[82:83] offset:4
	global_atomic_add_f32 v243, v32, s[82:83] offset:8
	global_atomic_add_f32 v243, v33, s[82:83] offset:12
	global_atomic_add_f32 v243, v26, s[82:83] offset:64
	global_atomic_add_f32 v243, v27, s[82:83] offset:68
	global_atomic_add_f32 v243, v28, s[82:83] offset:72
	global_atomic_add_f32 v243, v29, s[82:83] offset:76
	global_atomic_add_f32 v243, v22, s[82:83] offset:128
	global_atomic_add_f32 v243, v23, s[82:83] offset:132
	global_atomic_add_f32 v243, v24, s[82:83] offset:136
	global_atomic_add_f32 v243, v25, s[82:83] offset:140
	global_atomic_add_f32 v243, v18, s[82:83] offset:192
	global_atomic_add_f32 v243, v19, s[82:83] offset:196
	global_atomic_add_f32 v243, v20, s[82:83] offset:200
	global_atomic_add_f32 v243, v21, s[82:83] offset:204
	v_add_u32_e32 v243, 0x10000, v243
	global_atomic_add_f32 v243, v14, s[82:83] offset:0
	global_atomic_add_f32 v243, v15, s[82:83] offset:4
	global_atomic_add_f32 v243, v16, s[82:83] offset:8
	global_atomic_add_f32 v243, v17, s[82:83] offset:12
	global_atomic_add_f32 v243, v10, s[82:83] offset:64
	global_atomic_add_f32 v243, v11, s[82:83] offset:68
	global_atomic_add_f32 v243, v12, s[82:83] offset:72
	global_atomic_add_f32 v243, v13, s[82:83] offset:76
	global_atomic_add_f32 v243, v6, s[82:83] offset:128
	global_atomic_add_f32 v243, v7, s[82:83] offset:132
	global_atomic_add_f32 v243, v8, s[82:83] offset:136
	global_atomic_add_f32 v243, v9, s[82:83] offset:140
	global_atomic_add_f32 v243, v2, s[82:83] offset:192
	global_atomic_add_f32 v243, v3, s[82:83] offset:196
	global_atomic_add_f32 v243, v4, s[82:83] offset:200
	global_atomic_add_f32 v243, v5, s[82:83] offset:204
	v_add_u32_e32 v243, 0x10000, v243
.Lop0_done:
	s_mov_b64 s[10:11], exec
	s_branch .LBB0_1327

.Lop1_orig:
	s_cmp_lg_u32 s15, 0
	s_cbranch_scc1 .Lop1_done
	v_add_u32_e32 v242, 4, v167
	v_mul_u32_u24_e32 v242, 0x6000, v242
	v_add_u32_e32 v242, v242, v0
	v_lshlrev_b32_e32 v243, 12, v134
	v_add_u32_e32 v243, v243, v0
	global_load_dwordx4 v[130:133], v242, s[4:5] offset:0
	global_load_dwordx4 v[134:137], v242, s[4:5] offset:64
	global_load_dwordx4 v[138:141], v242, s[4:5] offset:128
	global_load_dwordx4 v[142:145], v242, s[4:5] offset:192
	v_add_u32_e32 v242, 0x60000, v242
	global_load_dwordx4 v[146:149], v242, s[4:5] offset:0
	global_load_dwordx4 v[150:153], v242, s[4:5] offset:64
	global_load_dwordx4 v[154:157], v242, s[4:5] offset:128
	global_load_dwordx4 v[158:161], v242, s[4:5] offset:192
	v_add_u32_e32 v242, 0x60000, v242
	global_load_dwordx4 v[162:165], v242, s[4:5] offset:0
	global_load_dwordx4 v[194:197], v242, s[4:5] offset:64
	global_load_dwordx4 v[198:201], v242, s[4:5] offset:128
	global_load_dwordx4 v[202:205], v242, s[4:5] offset:192
	v_add_u32_e32 v242, 0x60000, v242
	global_load_dwordx4 v[206:209], v242, s[4:5] offset:0
	global_load_dwordx4 v[210:213], v242, s[4:5] offset:64
	global_load_dwordx4 v[214:217], v242, s[4:5] offset:128
	global_load_dwordx4 v[218:221], v242, s[4:5] offset:192
	v_add_u32_e32 v242, 0x60000, v242
	s_waitcnt vmcnt(0)
	v_mul_f32_e32 v126, v126, v130
	v_mul_f32_e32 v127, v127, v131
	v_mul_f32_e32 v128, v128, v132
	v_mul_f32_e32 v129, v129, v133
	v_mul_f32_e32 v122, v122, v134
	v_mul_f32_e32 v123, v123, v135
	v_mul_f32_e32 v124, v124, v136
	v_mul_f32_e32 v125, v125, v137
	v_mul_f32_e32 v118, v118, v138
	v_mul_f32_e32 v119, v119, v139
	v_mul_f32_e32 v120, v120, v140
	v_mul_f32_e32 v121, v121, v141
	v_mul_f32_e32 v114, v114, v142
	v_mul_f32_e32 v115, v115, v143
	v_mul_f32_e32 v116, v116, v144
	v_mul_f32_e32 v117, v117, v145
	v_mul_f32_e32 v110, v110, v146
	v_mul_f32_e32 v111, v111, v147
	v_mul_f32_e32 v112, v112, v148
	v_mul_f32_e32 v113, v113, v149
	v_mul_f32_e32 v106, v106, v150
	v_mul_f32_e32 v107, v107, v151
	v_mul_f32_e32 v108, v108, v152
	v_mul_f32_e32 v109, v109, v153
	v_mul_f32_e32 v102, v102, v154
	v_mul_f32_e32 v103, v103, v155
	v_mul_f32_e32 v104, v104, v156
	v_mul_f32_e32 v105, v105, v157
	v_mul_f32_e32 v98, v98, v158
	v_mul_f32_e32 v99, v99, v159
	v_mul_f32_e32 v100, v100, v160
	v_mul_f32_e32 v101, v101, v161
	v_mul_f32_e32 v94, v94, v162
	v_mul_f32_e32 v95, v95, v163
	v_mul_f32_e32 v96, v96, v164
	v_mul_f32_e32 v97, v97, v165
	v_mul_f32_e32 v90, v90, v194
	v_mul_f32_e32 v91, v91, v195
	v_mul_f32_e32 v92, v92, v196
	v_mul_f32_e32 v93, v93, v197
	v_mul_f32_e32 v86, v86, v198
	v_mul_f32_e32 v87, v87, v199
	v_mul_f32_e32 v88, v88, v200
	v_mul_f32_e32 v89, v89, v201
	v_mul_f32_e32 v82, v82, v202
	v_mul_f32_e32 v83, v83, v203
	v_mul_f32_e32 v84, v84, v204
	v_mul_f32_e32 v85, v85, v205
	v_mul_f32_e32 v78, v78, v206
	v_mul_f32_e32 v79, v79, v207
	v_mul_f32_e32 v80, v80, v208
	v_mul_f32_e32 v81, v81, v209
	v_mul_f32_e32 v74, v74, v210
	v_mul_f32_e32 v75, v75, v211
	v_mul_f32_e32 v76, v76, v212
	v_mul_f32_e32 v77, v77, v213
	v_mul_f32_e32 v70, v70, v214
	v_mul_f32_e32 v71, v71, v215
	v_mul_f32_e32 v72, v72, v216
	v_mul_f32_e32 v73, v73, v217
	v_mul_f32_e32 v66, v66, v218
	v_mul_f32_e32 v67, v67, v219
	v_mul_f32_e32 v68, v68, v220
	v_mul_f32_e32 v69, v69, v221
	global_load_dwordx4 v[130:133], v242, s[4:5] offset:0
	global_load_dwordx4 v[134:137], v242, s[4:5] offset:64
	global_load_dwordx4 v[138:141], v242, s[4:5] offset:128
	global_load_dwordx4 v[142:145], v242, s[4:5] offset:192
	v_add_u32_e32 v242, 0x60000, v242
	global_load_dwordx4 v[146:149], v242, s[4:5] offset:0
	global_load_dwordx4 v[150:153], v242, s[4:5] offset:64
	global_load_dwordx4 v[154:157], v242, s[4:5] offset:128
	global_load_dwordx4 v[158:161], v242, s[4:5] offset:192
	v_add_u32_e32 v242, 0x60000, v242
	global_load_dwordx4 v[162:165], v242, s[4:5] offset:0
	global_load_dwordx4 v[194:197], v242, s[4:5] offset:64
	global_load_dwordx4 v[198:201], v242, s[4:5] offset:128
	global_load_dwordx4 v[202:205], v242, s[4:5] offset:192
	v_add_u32_e32 v242, 0x60000, v242
	global_load_dwordx4 v[206:209], v242, s[4:5] offset:0
	global_load_dwordx4 v[210:213], v242, s[4:5] offset:64
	global_load_dwordx4 v[214:217], v242, s[4:5] offset:128
	global_load_dwordx4 v[218:221], v242, s[4:5] offset:192
	v_add_u32_e32 v242, 0x60000, v242
	global_atomic_add_f32 v243, v126, s[82:83] offset:0
	global_atomic_add_f32 v243, v127, s[82:83] offset:4
	global_atomic_add_f32 v243, v128, s[82:83] offset:8
	global_atomic_add_f32 v243, v129, s[82:83] offset:12
	global_atomic_add_f32 v243, v122, s[82:83] offset:64
	global_atomic_add_f32 v243, v123, s[82:83] offset:68
	global_atomic_add_f32 v243, v124, s[82:83] offset:72
	global_atomic_add_f32 v243, v125, s[82:83] offset:76
	global_atomic_add_f32 v243, v118, s[82:83] offset:128
	global_atomic_add_f32 v243, v119, s[82:83] offset:132
	global_atomic_add_f32 v243, v120, s[82:83] offset:136
	global_atomic_add_f32 v243, v121, s[82:83] offset:140
	global_atomic_add_f32 v243, v114, s[82:83] offset:192
	global_atomic_add_f32 v243, v115, s[82:83] offset:196
	global_atomic_add_f32 v243, v116, s[82:83] offset:200
	global_atomic_add_f32 v243, v117, s[82:83] offset:204
	v_add_u32_e32 v243, 0x10000, v243
	global_atomic_add_f32 v243, v110, s[82:83] offset:0
	global_atomic_add_f32 v243, v111, s[82:83] offset:4
	global_atomic_add_f32 v243, v112, s[82:83] offset:8
	global_atomic_add_f32 v243, v113, s[82:83] offset:12
	global_atomic_add_f32 v243, v106, s[82:83] offset:64
	global_atomic_add_f32 v243, v107, s[82:83] offset:68
	global_atomic_add_f32 v243, v108, s[82:83] offset:72
	global_atomic_add_f32 v243, v109, s[82:83] offset:76
	global_atomic_add_f32 v243, v102, s[82:83] offset:128
	global_atomic_add_f32 v243, v103, s[82:83] offset:132
	global_atomic_add_f32 v243, v104, s[82:83] offset:136
	global_atomic_add_f32 v243, v105, s[82:83] offset:140
	global_atomic_add_f32 v243, v98, s[82:83] offset:192
	global_atomic_add_f32 v243, v99, s[82:83] offset:196
	global_atomic_add_f32 v243, v100, s[82:83] offset:200
	global_atomic_add_f32 v243, v101, s[82:83] offset:204
	v_add_u32_e32 v243, 0x10000, v243
	global_atomic_add_f32 v243, v94, s[82:83] offset:0
	global_atomic_add_f32 v243, v95, s[82:83] offset:4
	global_atomic_add_f32 v243, v96, s[82:83] offset:8
	global_atomic_add_f32 v243, v97, s[82:83] offset:12
	global_atomic_add_f32 v243, v90, s[82:83] offset:64
	global_atomic_add_f32 v243, v91, s[82:83] offset:68
	global_atomic_add_f32 v243, v92, s[82:83] offset:72
	global_atomic_add_f32 v243, v93, s[82:83] offset:76
	global_atomic_add_f32 v243, v86, s[82:83] offset:128
	global_atomic_add_f32 v243, v87, s[82:83] offset:132
	global_atomic_add_f32 v243, v88, s[82:83] offset:136
	global_atomic_add_f32 v243, v89, s[82:83] offset:140
	global_atomic_add_f32 v243, v82, s[82:83] offset:192
	global_atomic_add_f32 v243, v83, s[82:83] offset:196
	global_atomic_add_f32 v243, v84, s[82:83] offset:200
	global_atomic_add_f32 v243, v85, s[82:83] offset:204
	v_add_u32_e32 v243, 0x10000, v243
	global_atomic_add_f32 v243, v78, s[82:83] offset:0
	global_atomic_add_f32 v243, v79, s[82:83] offset:4
	global_atomic_add_f32 v243, v80, s[82:83] offset:8
	global_atomic_add_f32 v243, v81, s[82:83] offset:12
	global_atomic_add_f32 v243, v74, s[82:83] offset:64
	global_atomic_add_f32 v243, v75, s[82:83] offset:68
	global_atomic_add_f32 v243, v76, s[82:83] offset:72
	global_atomic_add_f32 v243, v77, s[82:83] offset:76
	global_atomic_add_f32 v243, v70, s[82:83] offset:128
	global_atomic_add_f32 v243, v71, s[82:83] offset:132
	global_atomic_add_f32 v243, v72, s[82:83] offset:136
	global_atomic_add_f32 v243, v73, s[82:83] offset:140
	global_atomic_add_f32 v243, v66, s[82:83] offset:192
	global_atomic_add_f32 v243, v67, s[82:83] offset:196
	global_atomic_add_f32 v243, v68, s[82:83] offset:200
	global_atomic_add_f32 v243, v69, s[82:83] offset:204
	v_add_u32_e32 v243, 0x10000, v243
	s_waitcnt vmcnt(63)
	v_mul_f32_e32 v62, v62, v130
	v_mul_f32_e32 v63, v63, v131
	v_mul_f32_e32 v64, v64, v132
	v_mul_f32_e32 v65, v65, v133
	v_mul_f32_e32 v58, v58, v134
	v_mul_f32_e32 v59, v59, v135
	v_mul_f32_e32 v60, v60, v136
	v_mul_f32_e32 v61, v61, v137
	v_mul_f32_e32 v54, v54, v138
	v_mul_f32_e32 v55, v55, v139
	v_mul_f32_e32 v56, v56, v140
	v_mul_f32_e32 v57, v57, v141
	v_mul_f32_e32 v50, v50, v142
	v_mul_f32_e32 v51, v51, v143
	v_mul_f32_e32 v52, v52, v144
	v_mul_f32_e32 v53, v53, v145
	v_mul_f32_e32 v46, v46, v146
	v_mul_f32_e32 v47, v47, v147
	v_mul_f32_e32 v48, v48, v148
	v_mul_f32_e32 v49, v49, v149
	v_mul_f32_e32 v42, v42, v150
	v_mul_f32_e32 v43, v43, v151
	v_mul_f32_e32 v44, v44, v152
	v_mul_f32_e32 v45, v45, v153
	v_mul_f32_e32 v38, v38, v154
	v_mul_f32_e32 v39, v39, v155
	v_mul_f32_e32 v40, v40, v156
	v_mul_f32_e32 v41, v41, v157
	v_mul_f32_e32 v34, v34, v158
	v_mul_f32_e32 v35, v35, v159
	v_mul_f32_e32 v36, v36, v160
	v_mul_f32_e32 v37, v37, v161
	v_mul_f32_e32 v30, v30, v162
	v_mul_f32_e32 v31, v31, v163
	v_mul_f32_e32 v32, v32, v164
	v_mul_f32_e32 v33, v33, v165
	v_mul_f32_e32 v26, v26, v194
	v_mul_f32_e32 v27, v27, v195
	v_mul_f32_e32 v28, v28, v196
	v_mul_f32_e32 v29, v29, v197
	v_mul_f32_e32 v22, v22, v198
	v_mul_f32_e32 v23, v23, v199
	v_mul_f32_e32 v24, v24, v200
	v_mul_f32_e32 v25, v25, v201
	v_mul_f32_e32 v18, v18, v202
	v_mul_f32_e32 v19, v19, v203
	v_mul_f32_e32 v20, v20, v204
	v_mul_f32_e32 v21, v21, v205
	v_mul_f32_e32 v14, v14, v206
	v_mul_f32_e32 v15, v15, v207
	v_mul_f32_e32 v16, v16, v208
	v_mul_f32_e32 v17, v17, v209
	v_mul_f32_e32 v10, v10, v210
	v_mul_f32_e32 v11, v11, v211
	v_mul_f32_e32 v12, v12, v212
	v_mul_f32_e32 v13, v13, v213
	v_mul_f32_e32 v6, v6, v214
	v_mul_f32_e32 v7, v7, v215
	v_mul_f32_e32 v8, v8, v216
	v_mul_f32_e32 v9, v9, v217
	v_mul_f32_e32 v2, v2, v218
	v_mul_f32_e32 v3, v3, v219
	v_mul_f32_e32 v4, v4, v220
	v_mul_f32_e32 v5, v5, v221
	global_atomic_add_f32 v243, v62, s[82:83] offset:0
	global_atomic_add_f32 v243, v63, s[82:83] offset:4
	global_atomic_add_f32 v243, v64, s[82:83] offset:8
	global_atomic_add_f32 v243, v65, s[82:83] offset:12
	global_atomic_add_f32 v243, v58, s[82:83] offset:64
	global_atomic_add_f32 v243, v59, s[82:83] offset:68
	global_atomic_add_f32 v243, v60, s[82:83] offset:72
	global_atomic_add_f32 v243, v61, s[82:83] offset:76
	global_atomic_add_f32 v243, v54, s[82:83] offset:128
	global_atomic_add_f32 v243, v55, s[82:83] offset:132
	global_atomic_add_f32 v243, v56, s[82:83] offset:136
	global_atomic_add_f32 v243, v57, s[82:83] offset:140
	global_atomic_add_f32 v243, v50, s[82:83] offset:192
	global_atomic_add_f32 v243, v51, s[82:83] offset:196
	global_atomic_add_f32 v243, v52, s[82:83] offset:200
	global_atomic_add_f32 v243, v53, s[82:83] offset:204
	v_add_u32_e32 v243, 0x10000, v243
	global_atomic_add_f32 v243, v46, s[82:83] offset:0
	global_atomic_add_f32 v243, v47, s[82:83] offset:4
	global_atomic_add_f32 v243, v48, s[82:83] offset:8
	global_atomic_add_f32 v243, v49, s[82:83] offset:12
	global_atomic_add_f32 v243, v42, s[82:83] offset:64
	global_atomic_add_f32 v243, v43, s[82:83] offset:68
	global_atomic_add_f32 v243, v44, s[82:83] offset:72
	global_atomic_add_f32 v243, v45, s[82:83] offset:76
	global_atomic_add_f32 v243, v38, s[82:83] offset:128
	global_atomic_add_f32 v243, v39, s[82:83] offset:132
	global_atomic_add_f32 v243, v40, s[82:83] offset:136
	global_atomic_add_f32 v243, v41, s[82:83] offset:140
	global_atomic_add_f32 v243, v34, s[82:83] offset:192
	global_atomic_add_f32 v243, v35, s[82:83] offset:196
	global_atomic_add_f32 v243, v36, s[82:83] offset:200
	global_atomic_add_f32 v243, v37, s[82:83] offset:204
	v_add_u32_e32 v243, 0x10000, v243
	global_atomic_add_f32 v243, v30, s[82:83] offset:0
	global_atomic_add_f32 v243, v31, s[82:83] offset:4
	global_atomic_add_f32 v243, v32, s[82:83] offset:8
	global_atomic_add_f32 v243, v33, s[82:83] offset:12
	global_atomic_add_f32 v243, v26, s[82:83] offset:64
	global_atomic_add_f32 v243, v27, s[82:83] offset:68
	global_atomic_add_f32 v243, v28, s[82:83] offset:72
	global_atomic_add_f32 v243, v29, s[82:83] offset:76
	global_atomic_add_f32 v243, v22, s[82:83] offset:128
	global_atomic_add_f32 v243, v23, s[82:83] offset:132
	global_atomic_add_f32 v243, v24, s[82:83] offset:136
	global_atomic_add_f32 v243, v25, s[82:83] offset:140
	global_atomic_add_f32 v243, v18, s[82:83] offset:192
	global_atomic_add_f32 v243, v19, s[82:83] offset:196
	global_atomic_add_f32 v243, v20, s[82:83] offset:200
	global_atomic_add_f32 v243, v21, s[82:83] offset:204
	v_add_u32_e32 v243, 0x10000, v243
	global_atomic_add_f32 v243, v14, s[82:83] offset:0
	global_atomic_add_f32 v243, v15, s[82:83] offset:4
	global_atomic_add_f32 v243, v16, s[82:83] offset:8
	global_atomic_add_f32 v243, v17, s[82:83] offset:12
	global_atomic_add_f32 v243, v10, s[82:83] offset:64
	global_atomic_add_f32 v243, v11, s[82:83] offset:68
	global_atomic_add_f32 v243, v12, s[82:83] offset:72
	global_atomic_add_f32 v243, v13, s[82:83] offset:76
	global_atomic_add_f32 v243, v6, s[82:83] offset:128
	global_atomic_add_f32 v243, v7, s[82:83] offset:132
	global_atomic_add_f32 v243, v8, s[82:83] offset:136
	global_atomic_add_f32 v243, v9, s[82:83] offset:140
	global_atomic_add_f32 v243, v2, s[82:83] offset:192
	global_atomic_add_f32 v243, v3, s[82:83] offset:196
	global_atomic_add_f32 v243, v4, s[82:83] offset:200
	global_atomic_add_f32 v243, v5, s[82:83] offset:204
	v_add_u32_e32 v243, 0x10000, v243

.Lop2_orig:
	s_cmp_lg_u32 s13, 0
	s_cbranch_scc1 .Lop2_done
	v_add_u32_e32 v242, 136, v167
	v_mul_u32_u24_e32 v242, 0x6000, v242
	v_add_u32_e32 v242, v242, v0
	v_lshlrev_b32_e32 v243, 12, v134
	v_add_u32_e32 v243, v243, v0
	global_load_dwordx4 v[130:133], v242, s[4:5] offset:0
	global_load_dwordx4 v[134:137], v242, s[4:5] offset:64
	global_load_dwordx4 v[138:141], v242, s[4:5] offset:128
	global_load_dwordx4 v[142:145], v242, s[4:5] offset:192
	v_add_u32_e32 v242, 0x60000, v242
	global_load_dwordx4 v[146:149], v242, s[4:5] offset:0
	global_load_dwordx4 v[150:153], v242, s[4:5] offset:64
	global_load_dwordx4 v[154:157], v242, s[4:5] offset:128
	global_load_dwordx4 v[158:161], v242, s[4:5] offset:192
	v_add_u32_e32 v242, 0x60000, v242
	global_load_dwordx4 v[162:165], v242, s[4:5] offset:0
	global_load_dwordx4 v[194:197], v242, s[4:5] offset:64
	global_load_dwordx4 v[198:201], v242, s[4:5] offset:128
	global_load_dwordx4 v[202:205], v242, s[4:5] offset:192
	v_add_u32_e32 v242, 0x60000, v242
	global_load_dwordx4 v[206:209], v242, s[4:5] offset:0
	global_load_dwordx4 v[210:213], v242, s[4:5] offset:64
	global_load_dwordx4 v[214:217], v242, s[4:5] offset:128
	global_load_dwordx4 v[218:221], v242, s[4:5] offset:192
	v_add_u32_e32 v242, 0x60000, v242
	s_waitcnt vmcnt(0)
	v_mul_f32_e32 v126, v126, v130
	v_mul_f32_e32 v127, v127, v131
	v_mul_f32_e32 v128, v128, v132
	v_mul_f32_e32 v129, v129, v133
	v_mul_f32_e32 v122, v122, v134
	v_mul_f32_e32 v123, v123, v135
	v_mul_f32_e32 v124, v124, v136
	v_mul_f32_e32 v125, v125, v137
	v_mul_f32_e32 v118, v118, v138
	v_mul_f32_e32 v119, v119, v139
	v_mul_f32_e32 v120, v120, v140
	v_mul_f32_e32 v121, v121, v141
	v_mul_f32_e32 v114, v114, v142
	v_mul_f32_e32 v115, v115, v143
	v_mul_f32_e32 v116, v116, v144
	v_mul_f32_e32 v117, v117, v145
	v_mul_f32_e32 v110, v110, v146
	v_mul_f32_e32 v111, v111, v147
	v_mul_f32_e32 v112, v112, v148
	v_mul_f32_e32 v113, v113, v149
	v_mul_f32_e32 v106, v106, v150
	v_mul_f32_e32 v107, v107, v151
	v_mul_f32_e32 v108, v108, v152
	v_mul_f32_e32 v109, v109, v153
	v_mul_f32_e32 v102, v102, v154
	v_mul_f32_e32 v103, v103, v155
	v_mul_f32_e32 v104, v104, v156
	v_mul_f32_e32 v105, v105, v157
	v_mul_f32_e32 v98, v98, v158
	v_mul_f32_e32 v99, v99, v159
	v_mul_f32_e32 v100, v100, v160
	v_mul_f32_e32 v101, v101, v161
	v_mul_f32_e32 v94, v94, v162
	v_mul_f32_e32 v95, v95, v163
	v_mul_f32_e32 v96, v96, v164
	v_mul_f32_e32 v97, v97, v165
	v_mul_f32_e32 v90, v90, v194
	v_mul_f32_e32 v91, v91, v195
	v_mul_f32_e32 v92, v92, v196
	v_mul_f32_e32 v93, v93, v197
	v_mul_f32_e32 v86, v86, v198
	v_mul_f32_e32 v87, v87, v199
	v_mul_f32_e32 v88, v88, v200
	v_mul_f32_e32 v89, v89, v201
	v_mul_f32_e32 v82, v82, v202
	v_mul_f32_e32 v83, v83, v203
	v_mul_f32_e32 v84, v84, v204
	v_mul_f32_e32 v85, v85, v205
	v_mul_f32_e32 v78, v78, v206
	v_mul_f32_e32 v79, v79, v207
	v_mul_f32_e32 v80, v80, v208
	v_mul_f32_e32 v81, v81, v209
	v_mul_f32_e32 v74, v74, v210
	v_mul_f32_e32 v75, v75, v211
	v_mul_f32_e32 v76, v76, v212
	v_mul_f32_e32 v77, v77, v213
	v_mul_f32_e32 v70, v70, v214
	v_mul_f32_e32 v71, v71, v215
	v_mul_f32_e32 v72, v72, v216
	v_mul_f32_e32 v73, v73, v217
	v_mul_f32_e32 v66, v66, v218
	v_mul_f32_e32 v67, v67, v219
	v_mul_f32_e32 v68, v68, v220
	v_mul_f32_e32 v69, v69, v221
	global_load_dwordx4 v[130:133], v242, s[4:5] offset:0
	global_load_dwordx4 v[134:137], v242, s[4:5] offset:64
	global_load_dwordx4 v[138:141], v242, s[4:5] offset:128
	global_load_dwordx4 v[142:145], v242, s[4:5] offset:192
	v_add_u32_e32 v242, 0x60000, v242
	global_load_dwordx4 v[146:149], v242, s[4:5] offset:0
	global_load_dwordx4 v[150:153], v242, s[4:5] offset:64
	global_load_dwordx4 v[154:157], v242, s[4:5] offset:128
	global_load_dwordx4 v[158:161], v242, s[4:5] offset:192
	v_add_u32_e32 v242, 0x60000, v242
	global_load_dwordx4 v[162:165], v242, s[4:5] offset:0
	global_load_dwordx4 v[194:197], v242, s[4:5] offset:64
	global_load_dwordx4 v[198:201], v242, s[4:5] offset:128
	global_load_dwordx4 v[202:205], v242, s[4:5] offset:192
	v_add_u32_e32 v242, 0x60000, v242
	global_load_dwordx4 v[206:209], v242, s[4:5] offset:0
	global_load_dwordx4 v[210:213], v242, s[4:5] offset:64
	global_load_dwordx4 v[214:217], v242, s[4:5] offset:128
	global_load_dwordx4 v[218:221], v242, s[4:5] offset:192
	v_add_u32_e32 v242, 0x60000, v242
	global_atomic_add_f32 v243, v126, s[82:83] offset:0
	global_atomic_add_f32 v243, v127, s[82:83] offset:4
	global_atomic_add_f32 v243, v128, s[82:83] offset:8
	global_atomic_add_f32 v243, v129, s[82:83] offset:12
	global_atomic_add_f32 v243, v122, s[82:83] offset:64
	global_atomic_add_f32 v243, v123, s[82:83] offset:68
	global_atomic_add_f32 v243, v124, s[82:83] offset:72
	global_atomic_add_f32 v243, v125, s[82:83] offset:76
	global_atomic_add_f32 v243, v118, s[82:83] offset:128
	global_atomic_add_f32 v243, v119, s[82:83] offset:132
	global_atomic_add_f32 v243, v120, s[82:83] offset:136
	global_atomic_add_f32 v243, v121, s[82:83] offset:140
	global_atomic_add_f32 v243, v114, s[82:83] offset:192
	global_atomic_add_f32 v243, v115, s[82:83] offset:196
	global_atomic_add_f32 v243, v116, s[82:83] offset:200
	global_atomic_add_f32 v243, v117, s[82:83] offset:204
	v_add_u32_e32 v243, 0x10000, v243
	global_atomic_add_f32 v243, v110, s[82:83] offset:0
	global_atomic_add_f32 v243, v111, s[82:83] offset:4
	global_atomic_add_f32 v243, v112, s[82:83] offset:8
	global_atomic_add_f32 v243, v113, s[82:83] offset:12
	global_atomic_add_f32 v243, v106, s[82:83] offset:64
	global_atomic_add_f32 v243, v107, s[82:83] offset:68
	global_atomic_add_f32 v243, v108, s[82:83] offset:72
	global_atomic_add_f32 v243, v109, s[82:83] offset:76
	global_atomic_add_f32 v243, v102, s[82:83] offset:128
	global_atomic_add_f32 v243, v103, s[82:83] offset:132
	global_atomic_add_f32 v243, v104, s[82:83] offset:136
	global_atomic_add_f32 v243, v105, s[82:83] offset:140
	global_atomic_add_f32 v243, v98, s[82:83] offset:192
	global_atomic_add_f32 v243, v99, s[82:83] offset:196
	global_atomic_add_f32 v243, v100, s[82:83] offset:200
	global_atomic_add_f32 v243, v101, s[82:83] offset:204
	v_add_u32_e32 v243, 0x10000, v243
	global_atomic_add_f32 v243, v94, s[82:83] offset:0
	global_atomic_add_f32 v243, v95, s[82:83] offset:4
	global_atomic_add_f32 v243, v96, s[82:83] offset:8
	global_atomic_add_f32 v243, v97, s[82:83] offset:12
	global_atomic_add_f32 v243, v90, s[82:83] offset:64
	global_atomic_add_f32 v243, v91, s[82:83] offset:68
	global_atomic_add_f32 v243, v92, s[82:83] offset:72
	global_atomic_add_f32 v243, v93, s[82:83] offset:76
	global_atomic_add_f32 v243, v86, s[82:83] offset:128
	global_atomic_add_f32 v243, v87, s[82:83] offset:132
	global_atomic_add_f32 v243, v88, s[82:83] offset:136
	global_atomic_add_f32 v243, v89, s[82:83] offset:140
	global_atomic_add_f32 v243, v82, s[82:83] offset:192
	global_atomic_add_f32 v243, v83, s[82:83] offset:196
	global_atomic_add_f32 v243, v84, s[82:83] offset:200
	global_atomic_add_f32 v243, v85, s[82:83] offset:204
	v_add_u32_e32 v243, 0x10000, v243
	global_atomic_add_f32 v243, v78, s[82:83] offset:0
	global_atomic_add_f32 v243, v79, s[82:83] offset:4
	global_atomic_add_f32 v243, v80, s[82:83] offset:8
	global_atomic_add_f32 v243, v81, s[82:83] offset:12
	global_atomic_add_f32 v243, v74, s[82:83] offset:64
	global_atomic_add_f32 v243, v75, s[82:83] offset:68
	global_atomic_add_f32 v243, v76, s[82:83] offset:72
	global_atomic_add_f32 v243, v77, s[82:83] offset:76
	global_atomic_add_f32 v243, v70, s[82:83] offset:128
	global_atomic_add_f32 v243, v71, s[82:83] offset:132
	global_atomic_add_f32 v243, v72, s[82:83] offset:136
	global_atomic_add_f32 v243, v73, s[82:83] offset:140
	global_atomic_add_f32 v243, v66, s[82:83] offset:192
	global_atomic_add_f32 v243, v67, s[82:83] offset:196
	global_atomic_add_f32 v243, v68, s[82:83] offset:200
	global_atomic_add_f32 v243, v69, s[82:83] offset:204
	v_add_u32_e32 v243, 0x10000, v243
	s_waitcnt vmcnt(63)
	v_mul_f32_e32 v62, v62, v130
	v_mul_f32_e32 v63, v63, v131
	v_mul_f32_e32 v64, v64, v132
	v_mul_f32_e32 v65, v65, v133
	v_mul_f32_e32 v58, v58, v134
	v_mul_f32_e32 v59, v59, v135
	v_mul_f32_e32 v60, v60, v136
	v_mul_f32_e32 v61, v61, v137
	v_mul_f32_e32 v54, v54, v138
	v_mul_f32_e32 v55, v55, v139
	v_mul_f32_e32 v56, v56, v140
	v_mul_f32_e32 v57, v57, v141
	v_mul_f32_e32 v50, v50, v142
	v_mul_f32_e32 v51, v51, v143
	v_mul_f32_e32 v52, v52, v144
	v_mul_f32_e32 v53, v53, v145
	v_mul_f32_e32 v46, v46, v146
	v_mul_f32_e32 v47, v47, v147
	v_mul_f32_e32 v48, v48, v148
	v_mul_f32_e32 v49, v49, v149
	v_mul_f32_e32 v42, v42, v150
	v_mul_f32_e32 v43, v43, v151
	v_mul_f32_e32 v44, v44, v152
	v_mul_f32_e32 v45, v45, v153
	v_mul_f32_e32 v38, v38, v154
	v_mul_f32_e32 v39, v39, v155
	v_mul_f32_e32 v40, v40, v156
	v_mul_f32_e32 v41, v41, v157
	v_mul_f32_e32 v34, v34, v158
	v_mul_f32_e32 v35, v35, v159
	v_mul_f32_e32 v36, v36, v160
	v_mul_f32_e32 v37, v37, v161
	v_mul_f32_e32 v30, v30, v162
	v_mul_f32_e32 v31, v31, v163
	v_mul_f32_e32 v32, v32, v164
	v_mul_f32_e32 v33, v33, v165
	v_mul_f32_e32 v26, v26, v194
	v_mul_f32_e32 v27, v27, v195
	v_mul_f32_e32 v28, v28, v196
	v_mul_f32_e32 v29, v29, v197
	v_mul_f32_e32 v22, v22, v198
	v_mul_f32_e32 v23, v23, v199
	v_mul_f32_e32 v24, v24, v200
	v_mul_f32_e32 v25, v25, v201
	v_mul_f32_e32 v18, v18, v202
	v_mul_f32_e32 v19, v19, v203
	v_mul_f32_e32 v20, v20, v204
	v_mul_f32_e32 v21, v21, v205
	v_mul_f32_e32 v14, v14, v206
	v_mul_f32_e32 v15, v15, v207
	v_mul_f32_e32 v16, v16, v208
	v_mul_f32_e32 v17, v17, v209
	v_mul_f32_e32 v10, v10, v210
	v_mul_f32_e32 v11, v11, v211
	v_mul_f32_e32 v12, v12, v212
	v_mul_f32_e32 v13, v13, v213
	v_mul_f32_e32 v6, v6, v214
	v_mul_f32_e32 v7, v7, v215
	v_mul_f32_e32 v8, v8, v216
	v_mul_f32_e32 v9, v9, v217
	v_mul_f32_e32 v2, v2, v218
	v_mul_f32_e32 v3, v3, v219
	v_mul_f32_e32 v4, v4, v220
	v_mul_f32_e32 v5, v5, v221
	global_atomic_add_f32 v243, v62, s[82:83] offset:0
	global_atomic_add_f32 v243, v63, s[82:83] offset:4
	global_atomic_add_f32 v243, v64, s[82:83] offset:8
	global_atomic_add_f32 v243, v65, s[82:83] offset:12
	global_atomic_add_f32 v243, v58, s[82:83] offset:64
	global_atomic_add_f32 v243, v59, s[82:83] offset:68
	global_atomic_add_f32 v243, v60, s[82:83] offset:72
	global_atomic_add_f32 v243, v61, s[82:83] offset:76
	global_atomic_add_f32 v243, v54, s[82:83] offset:128
	global_atomic_add_f32 v243, v55, s[82:83] offset:132
	global_atomic_add_f32 v243, v56, s[82:83] offset:136
	global_atomic_add_f32 v243, v57, s[82:83] offset:140
	global_atomic_add_f32 v243, v50, s[82:83] offset:192
	global_atomic_add_f32 v243, v51, s[82:83] offset:196
	global_atomic_add_f32 v243, v52, s[82:83] offset:200
	global_atomic_add_f32 v243, v53, s[82:83] offset:204
	v_add_u32_e32 v243, 0x10000, v243
	global_atomic_add_f32 v243, v46, s[82:83] offset:0
	global_atomic_add_f32 v243, v47, s[82:83] offset:4
	global_atomic_add_f32 v243, v48, s[82:83] offset:8
	global_atomic_add_f32 v243, v49, s[82:83] offset:12
	global_atomic_add_f32 v243, v42, s[82:83] offset:64
	global_atomic_add_f32 v243, v43, s[82:83] offset:68
	global_atomic_add_f32 v243, v44, s[82:83] offset:72
	global_atomic_add_f32 v243, v45, s[82:83] offset:76
	global_atomic_add_f32 v243, v38, s[82:83] offset:128
	global_atomic_add_f32 v243, v39, s[82:83] offset:132
	global_atomic_add_f32 v243, v40, s[82:83] offset:136
	global_atomic_add_f32 v243, v41, s[82:83] offset:140
	global_atomic_add_f32 v243, v34, s[82:83] offset:192
	global_atomic_add_f32 v243, v35, s[82:83] offset:196
	global_atomic_add_f32 v243, v36, s[82:83] offset:200
	global_atomic_add_f32 v243, v37, s[82:83] offset:204
	v_add_u32_e32 v243, 0x10000, v243
	global_atomic_add_f32 v243, v30, s[82:83] offset:0
	global_atomic_add_f32 v243, v31, s[82:83] offset:4
	global_atomic_add_f32 v243, v32, s[82:83] offset:8
	global_atomic_add_f32 v243, v33, s[82:83] offset:12
	global_atomic_add_f32 v243, v26, s[82:83] offset:64
	global_atomic_add_f32 v243, v27, s[82:83] offset:68
	global_atomic_add_f32 v243, v28, s[82:83] offset:72
	global_atomic_add_f32 v243, v29, s[82:83] offset:76
	global_atomic_add_f32 v243, v22, s[82:83] offset:128
	global_atomic_add_f32 v243, v23, s[82:83] offset:132
	global_atomic_add_f32 v243, v24, s[82:83] offset:136
	global_atomic_add_f32 v243, v25, s[82:83] offset:140
	global_atomic_add_f32 v243, v18, s[82:83] offset:192
	global_atomic_add_f32 v243, v19, s[82:83] offset:196
	global_atomic_add_f32 v243, v20, s[82:83] offset:200
	global_atomic_add_f32 v243, v21, s[82:83] offset:204
	v_add_u32_e32 v243, 0x10000, v243
	global_atomic_add_f32 v243, v14, s[82:83] offset:0
	global_atomic_add_f32 v243, v15, s[82:83] offset:4
	global_atomic_add_f32 v243, v16, s[82:83] offset:8
	global_atomic_add_f32 v243, v17, s[82:83] offset:12
	global_atomic_add_f32 v243, v10, s[82:83] offset:64
	global_atomic_add_f32 v243, v11, s[82:83] offset:68
	global_atomic_add_f32 v243, v12, s[82:83] offset:72
	global_atomic_add_f32 v243, v13, s[82:83] offset:76
	global_atomic_add_f32 v243, v6, s[82:83] offset:128
	global_atomic_add_f32 v243, v7, s[82:83] offset:132
	global_atomic_add_f32 v243, v8, s[82:83] offset:136
	global_atomic_add_f32 v243, v9, s[82:83] offset:140
	global_atomic_add_f32 v243, v2, s[82:83] offset:192
	global_atomic_add_f32 v243, v3, s[82:83] offset:196
	global_atomic_add_f32 v243, v4, s[82:83] offset:200
	global_atomic_add_f32 v243, v5, s[82:83] offset:204
	v_add_u32_e32 v243, 0x10000, v243
.Lop2_done:
	s_mov_b64 s[8:9], exec
	s_branch .LBB0_2752

.Lop3_orig:
	s_cmp_lg_u32 s15, 0
	s_cbranch_scc1 .Lop3_done
	v_add_u32_e32 v242, 136, v167
	v_mul_u32_u24_e32 v242, 0x6000, v242
	v_add_u32_e32 v242, v242, v0
	v_lshlrev_b32_e32 v243, 12, v134
	v_add_u32_e32 v243, v243, v0
	global_load_dwordx4 v[130:133], v242, s[4:5] offset:0
	global_load_dwordx4 v[134:137], v242, s[4:5] offset:64
	global_load_dwordx4 v[138:141], v242, s[4:5] offset:128
	global_load_dwordx4 v[142:145], v242, s[4:5] offset:192
	v_add_u32_e32 v242, 0x60000, v242
	global_load_dwordx4 v[146:149], v242, s[4:5] offset:0
	global_load_dwordx4 v[150:153], v242, s[4:5] offset:64
	global_load_dwordx4 v[154:157], v242, s[4:5] offset:128
	global_load_dwordx4 v[158:161], v242, s[4:5] offset:192
	v_add_u32_e32 v242, 0x60000, v242
	global_load_dwordx4 v[162:165], v242, s[4:5] offset:0
	global_load_dwordx4 v[194:197], v242, s[4:5] offset:64
	global_load_dwordx4 v[198:201], v242, s[4:5] offset:128
	global_load_dwordx4 v[202:205], v242, s[4:5] offset:192
	v_add_u32_e32 v242, 0x60000, v242
	global_load_dwordx4 v[206:209], v242, s[4:5] offset:0
	global_load_dwordx4 v[210:213], v242, s[4:5] offset:64
	global_load_dwordx4 v[214:217], v242, s[4:5] offset:128
	global_load_dwordx4 v[218:221], v242, s[4:5] offset:192
	v_add_u32_e32 v242, 0x60000, v242
	s_waitcnt vmcnt(0)
	v_mul_f32_e32 v126, v126, v130
	v_mul_f32_e32 v127, v127, v131
	v_mul_f32_e32 v128, v128, v132
	v_mul_f32_e32 v129, v129, v133
	v_mul_f32_e32 v122, v122, v134
	v_mul_f32_e32 v123, v123, v135
	v_mul_f32_e32 v124, v124, v136
	v_mul_f32_e32 v125, v125, v137
	v_mul_f32_e32 v118, v118, v138
	v_mul_f32_e32 v119, v119, v139
	v_mul_f32_e32 v120, v120, v140
	v_mul_f32_e32 v121, v121, v141
	v_mul_f32_e32 v114, v114, v142
	v_mul_f32_e32 v115, v115, v143
	v_mul_f32_e32 v116, v116, v144
	v_mul_f32_e32 v117, v117, v145
	v_mul_f32_e32 v110, v110, v146
	v_mul_f32_e32 v111, v111, v147
	v_mul_f32_e32 v112, v112, v148
	v_mul_f32_e32 v113, v113, v149
	v_mul_f32_e32 v106, v106, v150
	v_mul_f32_e32 v107, v107, v151
	v_mul_f32_e32 v108, v108, v152
	v_mul_f32_e32 v109, v109, v153
	v_mul_f32_e32 v102, v102, v154
	v_mul_f32_e32 v103, v103, v155
	v_mul_f32_e32 v104, v104, v156
	v_mul_f32_e32 v105, v105, v157
	v_mul_f32_e32 v98, v98, v158
	v_mul_f32_e32 v99, v99, v159
	v_mul_f32_e32 v100, v100, v160
	v_mul_f32_e32 v101, v101, v161
	v_mul_f32_e32 v94, v94, v162
	v_mul_f32_e32 v95, v95, v163
	v_mul_f32_e32 v96, v96, v164
	v_mul_f32_e32 v97, v97, v165
	v_mul_f32_e32 v90, v90, v194
	v_mul_f32_e32 v91, v91, v195
	v_mul_f32_e32 v92, v92, v196
	v_mul_f32_e32 v93, v93, v197
	v_mul_f32_e32 v86, v86, v198
	v_mul_f32_e32 v87, v87, v199
	v_mul_f32_e32 v88, v88, v200
	v_mul_f32_e32 v89, v89, v201
	v_mul_f32_e32 v82, v82, v202
	v_mul_f32_e32 v83, v83, v203
	v_mul_f32_e32 v84, v84, v204
	v_mul_f32_e32 v85, v85, v205
	v_mul_f32_e32 v78, v78, v206
	v_mul_f32_e32 v79, v79, v207
	v_mul_f32_e32 v80, v80, v208
	v_mul_f32_e32 v81, v81, v209
	v_mul_f32_e32 v74, v74, v210
	v_mul_f32_e32 v75, v75, v211
	v_mul_f32_e32 v76, v76, v212
	v_mul_f32_e32 v77, v77, v213
	v_mul_f32_e32 v70, v70, v214
	v_mul_f32_e32 v71, v71, v215
	v_mul_f32_e32 v72, v72, v216
	v_mul_f32_e32 v73, v73, v217
	v_mul_f32_e32 v66, v66, v218
	v_mul_f32_e32 v67, v67, v219
	v_mul_f32_e32 v68, v68, v220
	v_mul_f32_e32 v69, v69, v221
	global_load_dwordx4 v[130:133], v242, s[4:5] offset:0
	global_load_dwordx4 v[134:137], v242, s[4:5] offset:64
	global_load_dwordx4 v[138:141], v242, s[4:5] offset:128
	global_load_dwordx4 v[142:145], v242, s[4:5] offset:192
	v_add_u32_e32 v242, 0x60000, v242
	global_load_dwordx4 v[146:149], v242, s[4:5] offset:0
	global_load_dwordx4 v[150:153], v242, s[4:5] offset:64
	global_load_dwordx4 v[154:157], v242, s[4:5] offset:128
	global_load_dwordx4 v[158:161], v242, s[4:5] offset:192
	v_add_u32_e32 v242, 0x60000, v242
	global_load_dwordx4 v[162:165], v242, s[4:5] offset:0
	global_load_dwordx4 v[194:197], v242, s[4:5] offset:64
	global_load_dwordx4 v[198:201], v242, s[4:5] offset:128
	global_load_dwordx4 v[202:205], v242, s[4:5] offset:192
	v_add_u32_e32 v242, 0x60000, v242
	global_load_dwordx4 v[206:209], v242, s[4:5] offset:0
	global_load_dwordx4 v[210:213], v242, s[4:5] offset:64
	global_load_dwordx4 v[214:217], v242, s[4:5] offset:128
	global_load_dwordx4 v[218:221], v242, s[4:5] offset:192
	v_add_u32_e32 v242, 0x60000, v242
	global_atomic_add_f32 v243, v126, s[82:83] offset:0
	global_atomic_add_f32 v243, v127, s[82:83] offset:4
	global_atomic_add_f32 v243, v128, s[82:83] offset:8
	global_atomic_add_f32 v243, v129, s[82:83] offset:12
	global_atomic_add_f32 v243, v122, s[82:83] offset:64
	global_atomic_add_f32 v243, v123, s[82:83] offset:68
	global_atomic_add_f32 v243, v124, s[82:83] offset:72
	global_atomic_add_f32 v243, v125, s[82:83] offset:76
	global_atomic_add_f32 v243, v118, s[82:83] offset:128
	global_atomic_add_f32 v243, v119, s[82:83] offset:132
	global_atomic_add_f32 v243, v120, s[82:83] offset:136
	global_atomic_add_f32 v243, v121, s[82:83] offset:140
	global_atomic_add_f32 v243, v114, s[82:83] offset:192
	global_atomic_add_f32 v243, v115, s[82:83] offset:196
	global_atomic_add_f32 v243, v116, s[82:83] offset:200
	global_atomic_add_f32 v243, v117, s[82:83] offset:204
	v_add_u32_e32 v243, 0x10000, v243
	global_atomic_add_f32 v243, v110, s[82:83] offset:0
	global_atomic_add_f32 v243, v111, s[82:83] offset:4
	global_atomic_add_f32 v243, v112, s[82:83] offset:8
	global_atomic_add_f32 v243, v113, s[82:83] offset:12
	global_atomic_add_f32 v243, v106, s[82:83] offset:64
	global_atomic_add_f32 v243, v107, s[82:83] offset:68
	global_atomic_add_f32 v243, v108, s[82:83] offset:72
	global_atomic_add_f32 v243, v109, s[82:83] offset:76
	global_atomic_add_f32 v243, v102, s[82:83] offset:128
	global_atomic_add_f32 v243, v103, s[82:83] offset:132
	global_atomic_add_f32 v243, v104, s[82:83] offset:136
	global_atomic_add_f32 v243, v105, s[82:83] offset:140
	global_atomic_add_f32 v243, v98, s[82:83] offset:192
	global_atomic_add_f32 v243, v99, s[82:83] offset:196
	global_atomic_add_f32 v243, v100, s[82:83] offset:200
	global_atomic_add_f32 v243, v101, s[82:83] offset:204
	v_add_u32_e32 v243, 0x10000, v243
	global_atomic_add_f32 v243, v94, s[82:83] offset:0
	global_atomic_add_f32 v243, v95, s[82:83] offset:4
	global_atomic_add_f32 v243, v96, s[82:83] offset:8
	global_atomic_add_f32 v243, v97, s[82:83] offset:12
	global_atomic_add_f32 v243, v90, s[82:83] offset:64
	global_atomic_add_f32 v243, v91, s[82:83] offset:68
	global_atomic_add_f32 v243, v92, s[82:83] offset:72
	global_atomic_add_f32 v243, v93, s[82:83] offset:76
	global_atomic_add_f32 v243, v86, s[82:83] offset:128
	global_atomic_add_f32 v243, v87, s[82:83] offset:132
	global_atomic_add_f32 v243, v88, s[82:83] offset:136
	global_atomic_add_f32 v243, v89, s[82:83] offset:140
	global_atomic_add_f32 v243, v82, s[82:83] offset:192
	global_atomic_add_f32 v243, v83, s[82:83] offset:196
	global_atomic_add_f32 v243, v84, s[82:83] offset:200
	global_atomic_add_f32 v243, v85, s[82:83] offset:204
	v_add_u32_e32 v243, 0x10000, v243
	global_atomic_add_f32 v243, v78, s[82:83] offset:0
	global_atomic_add_f32 v243, v79, s[82:83] offset:4
	global_atomic_add_f32 v243, v80, s[82:83] offset:8
	global_atomic_add_f32 v243, v81, s[82:83] offset:12
	global_atomic_add_f32 v243, v74, s[82:83] offset:64
	global_atomic_add_f32 v243, v75, s[82:83] offset:68
	global_atomic_add_f32 v243, v76, s[82:83] offset:72
	global_atomic_add_f32 v243, v77, s[82:83] offset:76
	global_atomic_add_f32 v243, v70, s[82:83] offset:128
	global_atomic_add_f32 v243, v71, s[82:83] offset:132
	global_atomic_add_f32 v243, v72, s[82:83] offset:136
	global_atomic_add_f32 v243, v73, s[82:83] offset:140
	global_atomic_add_f32 v243, v66, s[82:83] offset:192
	global_atomic_add_f32 v243, v67, s[82:83] offset:196
	global_atomic_add_f32 v243, v68, s[82:83] offset:200
	global_atomic_add_f32 v243, v69, s[82:83] offset:204
	v_add_u32_e32 v243, 0x10000, v243
	s_waitcnt vmcnt(63)
	v_mul_f32_e32 v62, v62, v130
	v_mul_f32_e32 v63, v63, v131
	v_mul_f32_e32 v64, v64, v132
	v_mul_f32_e32 v65, v65, v133
	v_mul_f32_e32 v58, v58, v134
	v_mul_f32_e32 v59, v59, v135
	v_mul_f32_e32 v60, v60, v136
	v_mul_f32_e32 v61, v61, v137
	v_mul_f32_e32 v54, v54, v138
	v_mul_f32_e32 v55, v55, v139
	v_mul_f32_e32 v56, v56, v140
	v_mul_f32_e32 v57, v57, v141
	v_mul_f32_e32 v50, v50, v142
	v_mul_f32_e32 v51, v51, v143
	v_mul_f32_e32 v52, v52, v144
	v_mul_f32_e32 v53, v53, v145
	v_mul_f32_e32 v46, v46, v146
	v_mul_f32_e32 v47, v47, v147
	v_mul_f32_e32 v48, v48, v148
	v_mul_f32_e32 v49, v49, v149
	v_mul_f32_e32 v42, v42, v150
	v_mul_f32_e32 v43, v43, v151
	v_mul_f32_e32 v44, v44, v152
	v_mul_f32_e32 v45, v45, v153
	v_mul_f32_e32 v38, v38, v154
	v_mul_f32_e32 v39, v39, v155
	v_mul_f32_e32 v40, v40, v156
	v_mul_f32_e32 v41, v41, v157
	v_mul_f32_e32 v34, v34, v158
	v_mul_f32_e32 v35, v35, v159
	v_mul_f32_e32 v36, v36, v160
	v_mul_f32_e32 v37, v37, v161
	v_mul_f32_e32 v30, v30, v162
	v_mul_f32_e32 v31, v31, v163
	v_mul_f32_e32 v32, v32, v164
	v_mul_f32_e32 v33, v33, v165
	v_mul_f32_e32 v26, v26, v194
	v_mul_f32_e32 v27, v27, v195
	v_mul_f32_e32 v28, v28, v196
	v_mul_f32_e32 v29, v29, v197
	v_mul_f32_e32 v22, v22, v198
	v_mul_f32_e32 v23, v23, v199
	v_mul_f32_e32 v24, v24, v200
	v_mul_f32_e32 v25, v25, v201
	v_mul_f32_e32 v18, v18, v202
	v_mul_f32_e32 v19, v19, v203
	v_mul_f32_e32 v20, v20, v204
	v_mul_f32_e32 v21, v21, v205
	v_mul_f32_e32 v14, v14, v206
	v_mul_f32_e32 v15, v15, v207
	v_mul_f32_e32 v16, v16, v208
	v_mul_f32_e32 v17, v17, v209
	v_mul_f32_e32 v10, v10, v210
	v_mul_f32_e32 v11, v11, v211
	v_mul_f32_e32 v12, v12, v212
	v_mul_f32_e32 v13, v13, v213
	v_mul_f32_e32 v6, v6, v214
	v_mul_f32_e32 v7, v7, v215
	v_mul_f32_e32 v8, v8, v216
	v_mul_f32_e32 v9, v9, v217
	v_mul_f32_e32 v2, v2, v218
	v_mul_f32_e32 v3, v3, v219
	v_mul_f32_e32 v4, v4, v220
	v_mul_f32_e32 v5, v5, v221
	global_atomic_add_f32 v243, v62, s[82:83] offset:0
	global_atomic_add_f32 v243, v63, s[82:83] offset:4
	global_atomic_add_f32 v243, v64, s[82:83] offset:8
	global_atomic_add_f32 v243, v65, s[82:83] offset:12
	global_atomic_add_f32 v243, v58, s[82:83] offset:64
	global_atomic_add_f32 v243, v59, s[82:83] offset:68
	global_atomic_add_f32 v243, v60, s[82:83] offset:72
	global_atomic_add_f32 v243, v61, s[82:83] offset:76
	global_atomic_add_f32 v243, v54, s[82:83] offset:128
	global_atomic_add_f32 v243, v55, s[82:83] offset:132
	global_atomic_add_f32 v243, v56, s[82:83] offset:136
	global_atomic_add_f32 v243, v57, s[82:83] offset:140
	global_atomic_add_f32 v243, v50, s[82:83] offset:192
	global_atomic_add_f32 v243, v51, s[82:83] offset:196
	global_atomic_add_f32 v243, v52, s[82:83] offset:200
	global_atomic_add_f32 v243, v53, s[82:83] offset:204
	v_add_u32_e32 v243, 0x10000, v243
	global_atomic_add_f32 v243, v46, s[82:83] offset:0
	global_atomic_add_f32 v243, v47, s[82:83] offset:4
	global_atomic_add_f32 v243, v48, s[82:83] offset:8
	global_atomic_add_f32 v243, v49, s[82:83] offset:12
	global_atomic_add_f32 v243, v42, s[82:83] offset:64
	global_atomic_add_f32 v243, v43, s[82:83] offset:68
	global_atomic_add_f32 v243, v44, s[82:83] offset:72
	global_atomic_add_f32 v243, v45, s[82:83] offset:76
	global_atomic_add_f32 v243, v38, s[82:83] offset:128
	global_atomic_add_f32 v243, v39, s[82:83] offset:132
	global_atomic_add_f32 v243, v40, s[82:83] offset:136
	global_atomic_add_f32 v243, v41, s[82:83] offset:140
	global_atomic_add_f32 v243, v34, s[82:83] offset:192
	global_atomic_add_f32 v243, v35, s[82:83] offset:196
	global_atomic_add_f32 v243, v36, s[82:83] offset:200
	global_atomic_add_f32 v243, v37, s[82:83] offset:204
	v_add_u32_e32 v243, 0x10000, v243
	global_atomic_add_f32 v243, v30, s[82:83] offset:0
	global_atomic_add_f32 v243, v31, s[82:83] offset:4
	global_atomic_add_f32 v243, v32, s[82:83] offset:8
	global_atomic_add_f32 v243, v33, s[82:83] offset:12
	global_atomic_add_f32 v243, v26, s[82:83] offset:64
	global_atomic_add_f32 v243, v27, s[82:83] offset:68
	global_atomic_add_f32 v243, v28, s[82:83] offset:72
	global_atomic_add_f32 v243, v29, s[82:83] offset:76
	global_atomic_add_f32 v243, v22, s[82:83] offset:128
	global_atomic_add_f32 v243, v23, s[82:83] offset:132
	global_atomic_add_f32 v243, v24, s[82:83] offset:136
	global_atomic_add_f32 v243, v25, s[82:83] offset:140
	global_atomic_add_f32 v243, v18, s[82:83] offset:192
	global_atomic_add_f32 v243, v19, s[82:83] offset:196
	global_atomic_add_f32 v243, v20, s[82:83] offset:200
	global_atomic_add_f32 v243, v21, s[82:83] offset:204
	v_add_u32_e32 v243, 0x10000, v243
	global_atomic_add_f32 v243, v14, s[82:83] offset:0
	global_atomic_add_f32 v243, v15, s[82:83] offset:4
	global_atomic_add_f32 v243, v16, s[82:83] offset:8
	global_atomic_add_f32 v243, v17, s[82:83] offset:12
	global_atomic_add_f32 v243, v10, s[82:83] offset:64
	global_atomic_add_f32 v243, v11, s[82:83] offset:68
	global_atomic_add_f32 v243, v12, s[82:83] offset:72
	global_atomic_add_f32 v243, v13, s[82:83] offset:76
	global_atomic_add_f32 v243, v6, s[82:83] offset:128
	global_atomic_add_f32 v243, v7, s[82:83] offset:132
	global_atomic_add_f32 v243, v8, s[82:83] offset:136
	global_atomic_add_f32 v243, v9, s[82:83] offset:140
	global_atomic_add_f32 v243, v2, s[82:83] offset:192
	global_atomic_add_f32 v243, v3, s[82:83] offset:196
	global_atomic_add_f32 v243, v4, s[82:83] offset:200
	global_atomic_add_f32 v243, v5, s[82:83] offset:204
	v_add_u32_e32 v243, 0x10000, v243
